# NSA compressed/window passes: K-fragment LDS reads prefetched in a small ring ahead of the QK MFMA chain
# speedup vs baseline: 1.0027x; 1.0023x over previous
; #define MFMA32(a, b, c) __builtin_amdgcn_mfma_f32_32x32x16_bf16((a), (b), (c), 0, 0, 0)
; DI int crow(int i, int h) { return (i & 3) + 8 * (i >> 2) + 4 * h; }
; DI f32x16 scores_lds(const char* Ks, int half, const bf16x8 (&qf)[8], int r, int h) {
;   const char* kp = Ks + (half * 32 + r) * 272 + 16 * h;
;   f32x16 acc;
; #pragma unroll
;   for (int i = 0; i < 16; ++i) acc[i] = 0.f;
; #pragma unroll
;   for (int s = 0; s < 8; ++s) acc = MFMA32(*reinterpret_cast<const bf16x8*>(kp + 32 * s), qf[s], acc);
;   return acc;
; }
; template <int MODE> ...
;     ...
;       if (!full) {
; #pragma unroll
;         for (int i = 0; i < 16; ++i) {
;           const int key = key0 + crow(i, h);
;           bool v;
;           if (MODE <= 1) v = (16 * key + 31) <= t; else if (MODE == 2) v = key <= t; else v = (key <= t) && ((t - key) < 512);
;           acc[i] = v ? acc[i] : -1e30f;
;         }
;       }
.LBB0_105:
	ds_read_b128 v[2:5], v181
	ds_read_b128 v[50:53], v181 offset:32
	ds_read_b128 v[56:59], v181 offset:64
	ds_read_b128 v[60:63], v181 offset:96
	v_cmp_lt_i32_e32 vcc, s13, v46
	s_waitcnt lgkmcnt(3)
	v_mfma_f32_32x32x16_bf16 v[2:17], v[2:5], v[82:85], 0
	s_waitcnt lgkmcnt(2)
	v_mfma_f32_32x32x16_bf16 v[2:17], v[50:53], v[86:89], v[2:17]
	ds_read_b128 v[50:53], v181 offset:128
	s_waitcnt lgkmcnt(2)
	v_mfma_f32_32x32x16_bf16 v[2:17], v[56:59], v[90:93], v[2:17]
	ds_read_b128 v[56:59], v181 offset:160
	s_waitcnt lgkmcnt(2)
	v_mfma_f32_32x32x16_bf16 v[2:17], v[60:63], v[94:97], v[2:17]
	ds_read_b128 v[60:63], v181 offset:192
	s_waitcnt lgkmcnt(2)
	v_mfma_f32_32x32x16_bf16 v[2:17], v[50:53], v[98:101], v[2:17]
	ds_read_b128 v[50:53], v181 offset:224
	s_waitcnt lgkmcnt(2)
	v_mfma_f32_32x32x16_bf16 v[2:17], v[56:59], v[102:105], v[2:17]
	s_waitcnt lgkmcnt(1)
	v_mfma_f32_32x32x16_bf16 v[2:17], v[60:63], v[106:109], v[2:17]
	s_waitcnt lgkmcnt(0)
	v_mfma_f32_32x32x16_bf16 v[2:17], v[50:53], v[110:113], v[2:17]
	s_and_saveexec_b64 s[2:3], vcc
	s_cbranch_execz .LBB0_107
	v_add_u32_e32 v42, v199, v46
	v_add_u32_e32 v49, 31, v42
	v_cmp_le_i32_e32 vcc, v49, v0
	v_add_u32_e32 v49, 47, v42
	s_nop 5
	v_cndmask_b32_e32 v2, v209, v2, vcc
	v_cmp_le_i32_e32 vcc, v49, v0
	v_add_u32_e32 v49, 63, v42
	s_nop 0
	v_cndmask_b32_e32 v3, v209, v3, vcc
	v_cmp_le_i32_e32 vcc, v49, v0
	v_add_u32_e32 v49, 0x9f, v42
	s_nop 0
	v_cndmask_b32_e32 v4, v209, v4, vcc
	v_cmp_le_i32_e32 vcc, v42, v175
	s_nop 1
	v_cndmask_b32_e32 v5, v209, v5, vcc
	v_cmp_le_i32_e32 vcc, v49, v0
	v_add_u32_e32 v49, 0xaf, v42
	s_nop 0
	v_cndmask_b32_e32 v6, v209, v6, vcc
	v_cmp_le_i32_e32 vcc, v49, v0
	v_add_u32_e32 v49, 0xbf, v42
	s_nop 0
	v_cndmask_b32_e32 v7, v209, v7, vcc
	v_cmp_le_i32_e32 vcc, v49, v0
	v_add_u32_e32 v49, 0x11f, v42
	s_nop 0
	v_cndmask_b32_e32 v8, v209, v8, vcc
	v_cmp_le_i32_e32 vcc, v42, v196
	s_nop 1
	v_cndmask_b32_e32 v9, v209, v9, vcc
	v_cmp_le_i32_e32 vcc, v49, v0
	v_add_u32_e32 v49, 0x12f, v42
	s_nop 0
	v_cndmask_b32_e32 v10, v209, v10, vcc
	v_cmp_le_i32_e32 vcc, v49, v0
	v_add_u32_e32 v49, 0x13f, v42
	s_nop 0
	v_cndmask_b32_e32 v11, v209, v11, vcc
	v_cmp_le_i32_e32 vcc, v49, v0
	v_add_u32_e32 v49, 0x19f, v42
	s_nop 0
	v_cndmask_b32_e32 v12, v209, v12, vcc
	v_cmp_le_i32_e32 vcc, v42, v198
	s_nop 1
	v_cndmask_b32_e32 v13, v209, v13, vcc
	v_cmp_le_i32_e32 vcc, v49, v0
	v_add_u32_e32 v49, 0x1af, v42
	s_nop 0
	v_cndmask_b32_e32 v14, v209, v14, vcc
	v_cmp_le_i32_e32 vcc, v49, v0
	v_add_u32_e32 v49, 0x1bf, v42
	v_add_u32_e32 v42, 0x1cf, v42
	v_cndmask_b32_e32 v15, v209, v15, vcc
	v_cmp_le_i32_e32 vcc, v49, v0
	s_nop 1
	v_cndmask_b32_e32 v16, v209, v16, vcc
	v_cmp_le_i32_e32 vcc, v42, v0
	s_nop 1
	v_cndmask_b32_e32 v17, v209, v17, vcc

; #define MFMA32(a, b, c) __builtin_amdgcn_mfma_f32_32x32x16_bf16((a), (b), (c), 0, 0, 0)
; DI int crow(int i, int h) { return (i & 3) + 8 * (i >> 2) + 4 * h; }
; DI f32x16 scores_lds(const char* Ks, int half, const bf16x8 (&qf)[8], int r, int h) {
;   const char* kp = Ks + (half * 32 + r) * 272 + 16 * h;
;   f32x16 acc;
; #pragma unroll
;   for (int i = 0; i < 16; ++i) acc[i] = 0.f;
; #pragma unroll
;   for (int s = 0; s < 8; ++s) acc = MFMA32(*reinterpret_cast<const bf16x8*>(kp + 32 * s), qf[s], acc);
;   return acc;
; }
; template <int MODE> ...
;     ...
;       const int key0 = kb * 64 + half * 32;
;       bool full;
;       if (MODE <= 1) full = (16 * (key0 + 31) + 31) <= t0;
;       else if (MODE == 2) full = (key0 + 31) <= t0;
;       else full = ((key0 + 31) <= t0) && (key0 >= (t0 + 31 - 511));
;       if (!full) {
; #pragma unroll
;         for (int i = 0; i < 16; ++i) {
;           const int key = key0 + crow(i, h);
;           bool v;
;           if (MODE <= 1) v = (16 * key + 31) <= t; else if (MODE == 2) v = key <= t; else v = (key <= t) && ((t - key) < 512);
;           acc[i] = v ? acc[i] : -1e30f;
;         }
;       }
.LBB0_112:
	v_add_u32_e32 v47, v180, v150
	ds_read_b128 v[2:5], v47
	ds_read_b128 v[50:53], v47 offset:32
	ds_read_b128 v[56:59], v47 offset:64
	ds_read_b128 v[60:63], v47 offset:96
	s_waitcnt lgkmcnt(3)
	v_mfma_f32_32x32x16_bf16 v[2:17], v[2:5], v[82:85], 0
	s_waitcnt lgkmcnt(2)
	v_mfma_f32_32x32x16_bf16 v[2:17], v[50:53], v[86:89], v[2:17]
	ds_read_b128 v[50:53], v47 offset:128
	s_waitcnt lgkmcnt(2)
	v_mfma_f32_32x32x16_bf16 v[2:17], v[56:59], v[90:93], v[2:17]
	ds_read_b128 v[56:59], v47 offset:160
	s_waitcnt lgkmcnt(2)
	v_mfma_f32_32x32x16_bf16 v[2:17], v[60:63], v[94:97], v[2:17]
	ds_read_b128 v[60:63], v47 offset:192
	s_waitcnt lgkmcnt(2)
	v_mfma_f32_32x32x16_bf16 v[2:17], v[50:53], v[98:101], v[2:17]
	ds_read_b128 v[50:53], v47 offset:224
	s_waitcnt lgkmcnt(2)
	v_mfma_f32_32x32x16_bf16 v[2:17], v[56:59], v[102:105], v[2:17]
	s_waitcnt lgkmcnt(1)
	v_mfma_f32_32x32x16_bf16 v[2:17], v[60:63], v[106:109], v[2:17]
	v_add_u32_e32 v47, 0x400, v46
	v_cmp_lt_i32_e32 vcc, s13, v47
	s_waitcnt lgkmcnt(0)
	v_mfma_f32_32x32x16_bf16 v[2:17], v[50:53], v[110:113], v[2:17]
	s_and_saveexec_b64 s[2:3], vcc
	s_cbranch_execz .LBB0_114
	v_add_u32_e32 v47, v199, v46
	v_add_u32_e32 v50, 0x41f, v47
	v_cmp_le_i32_e32 vcc, v50, v0
	v_add_u32_e32 v50, 0x42f, v47
	v_add_u32_e32 v48, 0x400, v47
	s_nop 4
	v_cndmask_b32_e32 v2, v209, v2, vcc
	v_cmp_le_i32_e32 vcc, v50, v0
	v_add_u32_e32 v50, 0x43f, v47
	s_nop 0
	v_cndmask_b32_e32 v3, v209, v3, vcc
	v_cmp_le_i32_e32 vcc, v50, v0
	v_add_u32_e32 v50, 0x49f, v47
	s_nop 0
	v_cndmask_b32_e32 v4, v209, v4, vcc
	v_cmp_le_i32_e32 vcc, v48, v175
	s_nop 1
	v_cndmask_b32_e32 v5, v209, v5, vcc
	v_cmp_le_i32_e32 vcc, v50, v0
	v_add_u32_e32 v50, 0x4af, v47
	s_nop 0
	v_cndmask_b32_e32 v6, v209, v6, vcc
	v_cmp_le_i32_e32 vcc, v50, v0
	v_add_u32_e32 v50, 0x4bf, v47
	s_nop 0
	v_cndmask_b32_e32 v7, v209, v7, vcc
	v_cmp_le_i32_e32 vcc, v50, v0
	v_add_u32_e32 v50, 0x51f, v47
	s_nop 0
	v_cndmask_b32_e32 v8, v209, v8, vcc
	v_cmp_le_i32_e32 vcc, v48, v196
	s_nop 1
	v_cndmask_b32_e32 v9, v209, v9, vcc
	v_cmp_le_i32_e32 vcc, v50, v0
	v_add_u32_e32 v50, 0x52f, v47
	s_nop 0
	v_cndmask_b32_e32 v10, v209, v10, vcc
	v_cmp_le_i32_e32 vcc, v50, v0
	v_add_u32_e32 v50, 0x53f, v47
	s_nop 0
	v_cndmask_b32_e32 v11, v209, v11, vcc
	v_cmp_le_i32_e32 vcc, v50, v0
	s_nop 1
	v_cndmask_b32_e32 v12, v209, v12, vcc
	v_cmp_le_i32_e32 vcc, v48, v198
	v_add_u32_e32 v48, 0x59f, v47
	s_nop 0
	v_cndmask_b32_e32 v13, v209, v13, vcc
	v_cmp_le_i32_e32 vcc, v48, v0
	v_add_u32_e32 v48, 0x5af, v47
	s_nop 0
	v_cndmask_b32_e32 v14, v209, v14, vcc
	v_cmp_le_i32_e32 vcc, v48, v0
	v_add_u32_e32 v48, 0x5bf, v47
	v_add_u32_e32 v47, 0x5cf, v47
	v_cndmask_b32_e32 v15, v209, v15, vcc
	v_cmp_le_i32_e32 vcc, v48, v0
	s_nop 1
	v_cndmask_b32_e32 v16, v209, v16, vcc
	v_cmp_le_i32_e32 vcc, v47, v0
	s_nop 1
	v_cndmask_b32_e32 v17, v209, v17, vcc

; #define MFMA32(a, b, c) __builtin_amdgcn_mfma_f32_32x32x16_bf16((a), (b), (c), 0, 0, 0)
; DI int crow(int i, int h) { return (i & 3) + 8 * (i >> 2) + 4 * h; }
; DI f32x16 scores_lds(const char* Ks, int half, const bf16x8 (&qf)[8], int r, int h) {
;   const char* kp = Ks + (half * 32 + r) * 272 + 16 * h;
;   f32x16 acc;
; #pragma unroll
;   for (int i = 0; i < 16; ++i) acc[i] = 0.f;
; #pragma unroll
;   for (int s = 0; s < 8; ++s) acc = MFMA32(*reinterpret_cast<const bf16x8*>(kp + 32 * s), qf[s], acc);
;   return acc;
; }
; template <int MODE> ...
;     ...
;       const int key0 = kb * 64 + half * 32;
;       bool full;
;       if (MODE <= 1) full = (16 * (key0 + 31) + 31) <= t0;
;       else if (MODE == 2) full = (key0 + 31) <= t0;
;       else full = ((key0 + 31) <= t0) && (key0 >= (t0 + 31 - 511));
;       if (!full) {
; #pragma unroll
;         for (int i = 0; i < 16; ++i) {
;           const int key = key0 + crow(i, h);
;           bool v;
;           if (MODE <= 1) v = (16 * key + 31) <= t; else if (MODE == 2) v = key <= t; else v = (key <= t) && ((t - key) < 512);
;           acc[i] = v ? acc[i] : -1e30f;
;         }
;       }
.LBB0_123:
	ds_read_b128 v[66:69], v181
	ds_read_b128 v[238:241], v181 offset:32
	ds_read_b128 v[244:247], v181 offset:64
	v_cmp_lt_i32_e32 vcc, s13, v200
	s_waitcnt lgkmcnt(2)
	v_mfma_f32_32x32x16_bf16 v[66:81], v[66:69], v[82:85], 0
	s_waitcnt lgkmcnt(1)
	v_mfma_f32_32x32x16_bf16 v[66:81], v[238:241], v[86:89], v[66:81]
	ds_read_b128 v[238:241], v181 offset:96
	s_waitcnt lgkmcnt(1)
	v_mfma_f32_32x32x16_bf16 v[66:81], v[244:247], v[90:93], v[66:81]
	ds_read_b128 v[244:247], v181 offset:128
	s_waitcnt lgkmcnt(1)
	v_mfma_f32_32x32x16_bf16 v[66:81], v[238:241], v[94:97], v[66:81]
	ds_read_b128 v[238:241], v181 offset:160
	s_waitcnt lgkmcnt(1)
	v_mfma_f32_32x32x16_bf16 v[66:81], v[244:247], v[98:101], v[66:81]
	ds_read_b128 v[244:247], v181 offset:192
	s_waitcnt lgkmcnt(1)
	v_mfma_f32_32x32x16_bf16 v[66:81], v[238:241], v[102:105], v[66:81]
	ds_read_b128 v[238:241], v181 offset:224
	s_waitcnt lgkmcnt(1)
	v_mfma_f32_32x32x16_bf16 v[66:81], v[244:247], v[106:109], v[66:81]
	s_waitcnt lgkmcnt(0)
	v_mfma_f32_32x32x16_bf16 v[66:81], v[238:241], v[110:113], v[66:81]
	s_and_saveexec_b64 s[2:3], vcc
	s_cbranch_execz .LBB0_125
	v_add_u32_e32 v193, v199, v200
	v_add_u32_e32 v194, 31, v193
	v_cmp_le_i32_e32 vcc, v194, v0
	v_add_u32_e32 v194, 47, v193
	s_nop 5
	v_cndmask_b32_e32 v66, v209, v66, vcc
	v_cmp_le_i32_e32 vcc, v194, v0
	v_add_u32_e32 v194, 63, v193
	s_nop 0
	v_cndmask_b32_e32 v67, v209, v67, vcc
	v_cmp_le_i32_e32 vcc, v194, v0
	v_add_u32_e32 v194, 0x9f, v193
	s_nop 0
	v_cndmask_b32_e32 v68, v209, v68, vcc
	v_cmp_le_i32_e32 vcc, v193, v175
	s_nop 1
	v_cndmask_b32_e32 v69, v209, v69, vcc
	v_cmp_le_i32_e32 vcc, v194, v0
	v_add_u32_e32 v194, 0xaf, v193
	s_nop 0
	v_cndmask_b32_e32 v70, v209, v70, vcc
	v_cmp_le_i32_e32 vcc, v194, v0
	v_add_u32_e32 v194, 0xbf, v193
	s_nop 0
	v_cndmask_b32_e32 v71, v209, v71, vcc
	v_cmp_le_i32_e32 vcc, v194, v0
	v_add_u32_e32 v194, 0x11f, v193
	s_nop 0
	v_cndmask_b32_e32 v72, v209, v72, vcc
	v_cmp_le_i32_e32 vcc, v193, v196
	s_nop 1
	v_cndmask_b32_e32 v73, v209, v73, vcc
	v_cmp_le_i32_e32 vcc, v194, v0
	v_add_u32_e32 v194, 0x12f, v193
	s_nop 0
	v_cndmask_b32_e32 v74, v209, v74, vcc
	v_cmp_le_i32_e32 vcc, v194, v0
	v_add_u32_e32 v194, 0x13f, v193
	s_nop 0
	v_cndmask_b32_e32 v75, v209, v75, vcc
	v_cmp_le_i32_e32 vcc, v194, v0
	v_add_u32_e32 v194, 0x19f, v193
	s_nop 0
	v_cndmask_b32_e32 v76, v209, v76, vcc
	v_cmp_le_i32_e32 vcc, v193, v198
	s_nop 1
	v_cndmask_b32_e32 v77, v209, v77, vcc
	v_cmp_le_i32_e32 vcc, v194, v0
	v_add_u32_e32 v194, 0x1af, v193
	s_nop 0
	v_cndmask_b32_e32 v78, v209, v78, vcc
	v_cmp_le_i32_e32 vcc, v194, v0
	v_add_u32_e32 v194, 0x1bf, v193
	v_add_u32_e32 v193, 0x1cf, v193
	v_cndmask_b32_e32 v79, v209, v79, vcc
	v_cmp_le_i32_e32 vcc, v194, v0
	s_nop 1
	v_cndmask_b32_e32 v80, v209, v80, vcc
	v_cmp_le_i32_e32 vcc, v193, v0
	s_nop 1
	v_cndmask_b32_e32 v81, v209, v81, vcc

; #define MFMA32(a, b, c) __builtin_amdgcn_mfma_f32_32x32x16_bf16((a), (b), (c), 0, 0, 0)
; DI int crow(int i, int h) { return (i & 3) + 8 * (i >> 2) + 4 * h; }
; DI f32x16 scores_lds(const char* Ks, int half, const bf16x8 (&qf)[8], int r, int h) {
;   const char* kp = Ks + (half * 32 + r) * 272 + 16 * h;
;   f32x16 acc;
; #pragma unroll
;   for (int i = 0; i < 16; ++i) acc[i] = 0.f;
; #pragma unroll
;   for (int s = 0; s < 8; ++s) acc = MFMA32(*reinterpret_cast<const bf16x8*>(kp + 32 * s), qf[s], acc);
;   return acc;
; }
; template <int MODE> ...
;     ...
;       const int key0 = kb * 64 + half * 32;
;       bool full;
;       if (MODE <= 1) full = (16 * (key0 + 31) + 31) <= t0;
;       else if (MODE == 2) full = (key0 + 31) <= t0;
;       else full = ((key0 + 31) <= t0) && (key0 >= (t0 + 31 - 511));
;       if (!full) {
; #pragma unroll
;         for (int i = 0; i < 16; ++i) {
;           const int key = key0 + crow(i, h);
;           bool v;
;           if (MODE <= 1) v = (16 * key + 31) <= t; else if (MODE == 2) v = key <= t; else v = (key <= t) && ((t - key) < 512);
;           acc[i] = v ? acc[i] : -1e30f;
;         }
;       }
.LBB0_132:
	v_add_u32_e32 v214, v180, v150
	ds_read_b128 v[66:69], v214
	ds_read_b128 v[238:241], v214 offset:32
	ds_read_b128 v[244:247], v214 offset:64
	s_waitcnt lgkmcnt(2)
	v_mfma_f32_32x32x16_bf16 v[66:81], v[66:69], v[82:85], 0
	s_waitcnt lgkmcnt(1)
	v_mfma_f32_32x32x16_bf16 v[66:81], v[238:241], v[86:89], v[66:81]
	ds_read_b128 v[238:241], v214 offset:96
	s_waitcnt lgkmcnt(1)
	v_mfma_f32_32x32x16_bf16 v[66:81], v[244:247], v[90:93], v[66:81]
	ds_read_b128 v[244:247], v214 offset:128
	s_waitcnt lgkmcnt(1)
	v_mfma_f32_32x32x16_bf16 v[66:81], v[238:241], v[94:97], v[66:81]
	ds_read_b128 v[238:241], v214 offset:160
	s_waitcnt lgkmcnt(1)
	v_mfma_f32_32x32x16_bf16 v[66:81], v[244:247], v[98:101], v[66:81]
	ds_read_b128 v[244:247], v214 offset:192
	s_waitcnt lgkmcnt(1)
	v_mfma_f32_32x32x16_bf16 v[66:81], v[238:241], v[102:105], v[66:81]
	ds_read_b128 v[238:241], v214 offset:224
	s_waitcnt lgkmcnt(1)
	v_mfma_f32_32x32x16_bf16 v[66:81], v[244:247], v[106:109], v[66:81]
	v_add_u32_e32 v214, 0x400, v200
	v_cmp_lt_i32_e32 vcc, s13, v214
	s_waitcnt lgkmcnt(0)
	v_mfma_f32_32x32x16_bf16 v[66:81], v[238:241], v[110:113], v[66:81]
	s_and_saveexec_b64 s[2:3], vcc
	s_cbranch_execz .LBB0_134
	v_add_u32_e32 v214, v199, v200
	v_add_u32_e32 v216, 0x41f, v214
	v_cmp_le_i32_e32 vcc, v216, v0
	v_add_u32_e32 v216, 0x42f, v214
	v_add_u32_e32 v215, 0x400, v214
	s_nop 4
	v_cndmask_b32_e32 v66, v209, v66, vcc
	v_cmp_le_i32_e32 vcc, v216, v0
	v_add_u32_e32 v216, 0x43f, v214
	s_nop 0
	v_cndmask_b32_e32 v67, v209, v67, vcc
	v_cmp_le_i32_e32 vcc, v216, v0
	v_add_u32_e32 v216, 0x49f, v214
	s_nop 0
	v_cndmask_b32_e32 v68, v209, v68, vcc
	v_cmp_le_i32_e32 vcc, v215, v175
	s_nop 1
	v_cndmask_b32_e32 v69, v209, v69, vcc
	v_cmp_le_i32_e32 vcc, v216, v0
	v_add_u32_e32 v216, 0x4af, v214
	s_nop 0
	v_cndmask_b32_e32 v70, v209, v70, vcc
	v_cmp_le_i32_e32 vcc, v216, v0
	v_add_u32_e32 v216, 0x4bf, v214
	s_nop 0
	v_cndmask_b32_e32 v71, v209, v71, vcc
	v_cmp_le_i32_e32 vcc, v216, v0
	v_add_u32_e32 v216, 0x51f, v214
	s_nop 0
	v_cndmask_b32_e32 v72, v209, v72, vcc
	v_cmp_le_i32_e32 vcc, v215, v196
	s_nop 1
	v_cndmask_b32_e32 v73, v209, v73, vcc
	v_cmp_le_i32_e32 vcc, v216, v0
	v_add_u32_e32 v216, 0x52f, v214
	s_nop 0
	v_cndmask_b32_e32 v74, v209, v74, vcc
	v_cmp_le_i32_e32 vcc, v216, v0
	v_add_u32_e32 v216, 0x53f, v214
	s_nop 0
	v_cndmask_b32_e32 v75, v209, v75, vcc
	v_cmp_le_i32_e32 vcc, v216, v0
	s_nop 1
	v_cndmask_b32_e32 v76, v209, v76, vcc
	v_cmp_le_i32_e32 vcc, v215, v198
	v_add_u32_e32 v215, 0x59f, v214
	s_nop 0
	v_cndmask_b32_e32 v77, v209, v77, vcc
	v_cmp_le_i32_e32 vcc, v215, v0
	v_add_u32_e32 v215, 0x5af, v214
	s_nop 0
	v_cndmask_b32_e32 v78, v209, v78, vcc
	v_cmp_le_i32_e32 vcc, v215, v0
	v_add_u32_e32 v215, 0x5bf, v214
	v_add_u32_e32 v214, 0x5cf, v214
	v_cndmask_b32_e32 v79, v209, v79, vcc
	v_cmp_le_i32_e32 vcc, v215, v0
	s_nop 1
	v_cndmask_b32_e32 v80, v209, v80, vcc
	v_cmp_le_i32_e32 vcc, v214, v0
	s_nop 1
	v_cndmask_b32_e32 v81, v209, v81, vcc

; #define MFMA32(a, b, c) __builtin_amdgcn_mfma_f32_32x32x16_bf16((a), (b), (c), 0, 0, 0)
; DI int crow(int i, int h) { return (i & 3) + 8 * (i >> 2) + 4 * h; }
; DI f32x16 scores_lds(const char* Ks, int half, const bf16x8 (&qf)[8], int r, int h) {
;   const char* kp = Ks + (half * 32 + r) * 272 + 16 * h;
;   f32x16 acc;
; #pragma unroll
;   for (int i = 0; i < 16; ++i) acc[i] = 0.f;
; #pragma unroll
;   for (int s = 0; s < 8; ++s) acc = MFMA32(*reinterpret_cast<const bf16x8*>(kp + 32 * s), qf[s], acc);
;   return acc;
; }
; template <int MODE> ...
;     ...
;       const int key0 = kb * 64 + half * 32;
;       bool full;
;       if (MODE <= 1) full = (16 * (key0 + 31) + 31) <= t0;
;       else if (MODE == 2) full = (key0 + 31) <= t0;
;       else full = ((key0 + 31) <= t0) && (key0 >= (t0 + 31 - 511));
;       if (!full) {
; #pragma unroll
;         for (int i = 0; i < 16; ++i) {
;           const int key = key0 + crow(i, h);
;           bool v;
;           if (MODE <= 1) v = (16 * key + 31) <= t; else if (MODE == 2) v = key <= t; else v = (key <= t) && ((t - key) < 512);
;           acc[i] = v ? acc[i] : -1e30f;
;         }
;       }
.LBB0_195:
	ds_read_b128 v[66:69], v181
	ds_read_b128 v[168:171], v181 offset:32
	ds_read_b128 v[238:241], v181 offset:64
	ds_read_b128 v[242:245], v181 offset:96
	v_add_u32_e32 v166, s13, v162
	v_add_u32_e32 v165, 31, v166
	v_cmp_lt_i32_e32 vcc, s21, v165
	v_cmp_gt_i32_e64 s[0:1], s9, v166
	s_or_b64 s[0:1], vcc, s[0:1]
	s_waitcnt lgkmcnt(3)
	v_mfma_f32_32x32x16_bf16 v[66:81], v[66:69], v[82:85], 0
	s_waitcnt lgkmcnt(2)
	v_mfma_f32_32x32x16_bf16 v[66:81], v[168:171], v[86:89], v[66:81]
	ds_read_b128 v[168:171], v181 offset:128
	s_waitcnt lgkmcnt(2)
	v_mfma_f32_32x32x16_bf16 v[66:81], v[238:241], v[90:93], v[66:81]
	ds_read_b128 v[238:241], v181 offset:160
	s_waitcnt lgkmcnt(2)
	v_mfma_f32_32x32x16_bf16 v[66:81], v[242:245], v[94:97], v[66:81]
	ds_read_b128 v[242:245], v181 offset:192
	s_waitcnt lgkmcnt(2)
	v_mfma_f32_32x32x16_bf16 v[66:81], v[168:171], v[98:101], v[66:81]
	ds_read_b128 v[168:171], v181 offset:224
	s_waitcnt lgkmcnt(2)
	v_mfma_f32_32x32x16_bf16 v[66:81], v[238:241], v[102:105], v[66:81]
	s_waitcnt lgkmcnt(1)
	v_mfma_f32_32x32x16_bf16 v[66:81], v[242:245], v[106:109], v[66:81]
	s_waitcnt lgkmcnt(0)
	v_mfma_f32_32x32x16_bf16 v[66:81], v[168:171], v[110:113], v[66:81]
	s_and_saveexec_b64 s[2:3], s[0:1]
	s_cbranch_execz .LBB0_197
	v_add_u32_e32 v165, s13, v163
	v_cmp_le_i32_e32 vcc, v165, v0
	v_cmp_gt_i32_e64 s[0:1], v165, v146
	v_add_u32_e32 v168, s13, v164
	s_and_b64 vcc, vcc, s[0:1]
	v_add_u32_e32 v168, 0xffffe020, v168
	s_nop 3
	v_cndmask_b32_e32 v66, v209, v66, vcc
	v_cmp_lt_i32_e32 vcc, v165, v0
	v_cmp_lt_i32_e64 s[0:1], s57, v168
	s_and_b64 vcc, vcc, s[0:1]
	v_add_u32_e32 v168, 2, v165
	v_cndmask_b32_e32 v67, v209, v67, vcc
	v_cmp_le_i32_e32 vcc, v168, v0
	v_cmp_gt_i32_e64 s[0:1], v168, v146
	s_and_b64 vcc, vcc, s[0:1]
	v_add_u32_e32 v168, 3, v165
	v_cndmask_b32_e32 v68, v209, v68, vcc
	v_cmp_le_i32_e32 vcc, v168, v0
	v_cmp_gt_i32_e64 s[0:1], v168, v146
	s_and_b64 vcc, vcc, s[0:1]
	v_add_u32_e32 v168, 8, v165
	v_cndmask_b32_e32 v69, v209, v69, vcc
	v_cmp_le_i32_e32 vcc, v168, v0
	v_cmp_gt_i32_e64 s[0:1], v168, v146
	s_and_b64 vcc, vcc, s[0:1]
	v_add_u32_e32 v168, 9, v165
	v_cndmask_b32_e32 v70, v209, v70, vcc
	v_cmp_le_i32_e32 vcc, v168, v0
	v_cmp_gt_i32_e64 s[0:1], v168, v146
	s_and_b64 vcc, vcc, s[0:1]
	v_add_u32_e32 v168, 10, v165
	v_cndmask_b32_e32 v71, v209, v71, vcc
	v_cmp_le_i32_e32 vcc, v168, v0
	v_cmp_gt_i32_e64 s[0:1], v168, v146
	s_and_b64 vcc, vcc, s[0:1]
	v_add_u32_e32 v168, 11, v165
	v_cndmask_b32_e32 v72, v209, v72, vcc
	v_cmp_le_i32_e32 vcc, v168, v0
	v_cmp_gt_i32_e64 s[0:1], v168, v146
	s_and_b64 vcc, vcc, s[0:1]
	v_add_u32_e32 v168, 16, v165
	v_cndmask_b32_e32 v73, v209, v73, vcc
	v_cmp_le_i32_e32 vcc, v168, v0
	v_cmp_gt_i32_e64 s[0:1], v168, v146
	s_and_b64 vcc, vcc, s[0:1]
	v_add_u32_e32 v168, 17, v165
	v_cndmask_b32_e32 v74, v209, v74, vcc
	v_cmp_le_i32_e32 vcc, v168, v0
	v_cmp_gt_i32_e64 s[0:1], v168, v146
	s_and_b64 vcc, vcc, s[0:1]
	v_add_u32_e32 v168, 18, v165
	v_cndmask_b32_e32 v75, v209, v75, vcc
	v_cmp_le_i32_e32 vcc, v168, v0
	v_cmp_gt_i32_e64 s[0:1], v168, v146
	s_and_b64 vcc, vcc, s[0:1]
	v_add_u32_e32 v168, 19, v165
	v_cndmask_b32_e32 v76, v209, v76, vcc
	v_cmp_le_i32_e32 vcc, v168, v0
	v_cmp_gt_i32_e64 s[0:1], v168, v146
	s_and_b64 vcc, vcc, s[0:1]
	v_add_u32_e32 v168, 24, v165
	v_cndmask_b32_e32 v77, v209, v77, vcc
	v_cmp_le_i32_e32 vcc, v168, v0
	v_cmp_gt_i32_e64 s[0:1], v168, v146
	s_and_b64 vcc, vcc, s[0:1]
	v_add_u32_e32 v168, 25, v165
	v_cndmask_b32_e32 v78, v209, v78, vcc
	v_cmp_le_i32_e32 vcc, v168, v0
	v_cmp_gt_i32_e64 s[0:1], v168, v146
	s_and_b64 vcc, vcc, s[0:1]
	v_add_u32_e32 v168, 26, v165
	v_cndmask_b32_e32 v79, v209, v79, vcc
	v_cmp_le_i32_e32 vcc, v168, v0
	v_cmp_gt_i32_e64 s[0:1], v168, v146
	s_and_b64 vcc, vcc, s[0:1]
	v_add_u32_e32 v165, 27, v165
	v_cndmask_b32_e32 v80, v209, v80, vcc
	v_cmp_le_i32_e32 vcc, v165, v0
	v_cmp_gt_i32_e64 s[0:1], v165, v146
	s_and_b64 vcc, vcc, s[0:1]
	v_cndmask_b32_e32 v81, v209, v81, vcc

; #define MFMA32(a, b, c) __builtin_amdgcn_mfma_f32_32x32x16_bf16((a), (b), (c), 0, 0, 0)
; DI int crow(int i, int h) { return (i & 3) + 8 * (i >> 2) + 4 * h; }
; DI f32x16 scores_lds(const char* Ks, int half, const bf16x8 (&qf)[8], int r, int h) {
;   const char* kp = Ks + (half * 32 + r) * 272 + 16 * h;
;   f32x16 acc;
; #pragma unroll
;   for (int i = 0; i < 16; ++i) acc[i] = 0.f;
; #pragma unroll
;   for (int s = 0; s < 8; ++s) acc = MFMA32(*reinterpret_cast<const bf16x8*>(kp + 32 * s), qf[s], acc);
;   return acc;
; }
; template <int MODE> ...
;     ...
;       const int key0 = kb * 64 + half * 32;
;       bool full;
;       if (MODE <= 1) full = (16 * (key0 + 31) + 31) <= t0;
;       else if (MODE == 2) full = (key0 + 31) <= t0;
;       else full = ((key0 + 31) <= t0) && (key0 >= (t0 + 31 - 511));
;       if (!full) {
; #pragma unroll
;         for (int i = 0; i < 16; ++i) {
;           const int key = key0 + crow(i, h);
;           bool v;
;           if (MODE <= 1) v = (16 * key + 31) <= t; else if (MODE == 2) v = key <= t; else v = (key <= t) && ((t - key) < 512);
;           acc[i] = v ? acc[i] : -1e30f;
;         }
;       }
.LBB0_204:
	v_add_u32_e32 v167, v180, v150
	ds_read_b128 v[66:69], v167
	ds_read_b128 v[168:171], v167 offset:32
	ds_read_b128 v[238:241], v167 offset:64
	ds_read_b128 v[242:245], v167 offset:96
	s_waitcnt lgkmcnt(3)
	v_mfma_f32_32x32x16_bf16 v[66:81], v[66:69], v[82:85], 0
	s_waitcnt lgkmcnt(2)
	v_mfma_f32_32x32x16_bf16 v[66:81], v[168:171], v[86:89], v[66:81]
	ds_read_b128 v[168:171], v167 offset:128
	s_waitcnt lgkmcnt(2)
	v_mfma_f32_32x32x16_bf16 v[66:81], v[238:241], v[90:93], v[66:81]
	ds_read_b128 v[238:241], v167 offset:160
	s_waitcnt lgkmcnt(2)
	v_mfma_f32_32x32x16_bf16 v[66:81], v[242:245], v[94:97], v[66:81]
	ds_read_b128 v[242:245], v167 offset:192
	s_waitcnt lgkmcnt(2)
	v_mfma_f32_32x32x16_bf16 v[66:81], v[168:171], v[98:101], v[66:81]
	ds_read_b128 v[168:171], v167 offset:224
	s_waitcnt lgkmcnt(2)
	v_mfma_f32_32x32x16_bf16 v[66:81], v[238:241], v[102:105], v[66:81]
	s_waitcnt lgkmcnt(1)
	v_mfma_f32_32x32x16_bf16 v[66:81], v[242:245], v[106:109], v[66:81]
	v_add_u32_e32 v167, 64, v166
	v_add_u32_e32 v166, 0x5f, v166
	v_cmp_lt_i32_e32 vcc, s21, v166
	v_cmp_gt_i32_e64 s[0:1], s9, v167
	s_or_b64 s[0:1], vcc, s[0:1]
	s_waitcnt lgkmcnt(0)
	v_mfma_f32_32x32x16_bf16 v[66:81], v[168:171], v[110:113], v[66:81]
	s_and_saveexec_b64 s[2:3], s[0:1]
	s_cbranch_execz .LBB0_206
	v_add_u32_e32 v166, s13, v163
	v_add_u32_e32 v167, 64, v166
	v_cmp_le_i32_e32 vcc, v167, v0
	v_cmp_gt_i32_e64 s[0:1], v167, v146
	s_and_b64 vcc, vcc, s[0:1]
	s_nop 4
	v_cndmask_b32_e32 v66, v209, v66, vcc
	v_cmp_lt_i32_e32 vcc, v167, v0
	v_add_u32_e32 v167, s13, v164
	v_add_u32_e32 v167, 0xffffe060, v167
	v_cmp_lt_i32_e64 s[0:1], s57, v167
	s_and_b64 vcc, vcc, s[0:1]
	v_add_u32_e32 v167, 0x42, v166
	v_cndmask_b32_e32 v67, v209, v67, vcc
	v_cmp_le_i32_e32 vcc, v167, v0
	v_cmp_gt_i32_e64 s[0:1], v167, v146
	s_and_b64 vcc, vcc, s[0:1]
	v_add_u32_e32 v167, 0x43, v166
	v_cndmask_b32_e32 v68, v209, v68, vcc
	v_cmp_le_i32_e32 vcc, v167, v0
	v_cmp_gt_i32_e64 s[0:1], v167, v146
	s_and_b64 vcc, vcc, s[0:1]
	v_add_u32_e32 v167, 0x48, v166
	v_cndmask_b32_e32 v69, v209, v69, vcc
	v_cmp_le_i32_e32 vcc, v167, v0
	v_cmp_gt_i32_e64 s[0:1], v167, v146
	s_and_b64 vcc, vcc, s[0:1]
	v_add_u32_e32 v167, 0x49, v166
	v_cndmask_b32_e32 v70, v209, v70, vcc
	v_cmp_le_i32_e32 vcc, v167, v0
	v_cmp_gt_i32_e64 s[0:1], v167, v146
	s_and_b64 vcc, vcc, s[0:1]
	v_add_u32_e32 v167, 0x4a, v166
	v_cndmask_b32_e32 v71, v209, v71, vcc
	v_cmp_le_i32_e32 vcc, v167, v0
	v_cmp_gt_i32_e64 s[0:1], v167, v146
	s_and_b64 vcc, vcc, s[0:1]
	v_add_u32_e32 v167, 0x4b, v166
	v_cndmask_b32_e32 v72, v209, v72, vcc
	v_cmp_le_i32_e32 vcc, v167, v0
	v_cmp_gt_i32_e64 s[0:1], v167, v146
	s_and_b64 vcc, vcc, s[0:1]
	v_add_u32_e32 v167, 0x50, v166
	v_cndmask_b32_e32 v73, v209, v73, vcc
	v_cmp_le_i32_e32 vcc, v167, v0
	v_cmp_gt_i32_e64 s[0:1], v167, v146
	s_and_b64 vcc, vcc, s[0:1]
	v_add_u32_e32 v167, 0x51, v166
	v_cndmask_b32_e32 v74, v209, v74, vcc
	v_cmp_le_i32_e32 vcc, v167, v0
	v_cmp_gt_i32_e64 s[0:1], v167, v146
	s_and_b64 vcc, vcc, s[0:1]
	v_add_u32_e32 v167, 0x52, v166
	v_cndmask_b32_e32 v75, v209, v75, vcc
	v_cmp_le_i32_e32 vcc, v167, v0
	v_cmp_gt_i32_e64 s[0:1], v167, v146
	s_and_b64 vcc, vcc, s[0:1]
	v_add_u32_e32 v167, 0x53, v166
	v_cndmask_b32_e32 v76, v209, v76, vcc
	v_cmp_le_i32_e32 vcc, v167, v0
	v_cmp_gt_i32_e64 s[0:1], v167, v146
	s_and_b64 vcc, vcc, s[0:1]
	v_add_u32_e32 v167, 0x58, v166
	v_cndmask_b32_e32 v77, v209, v77, vcc
	v_cmp_le_i32_e32 vcc, v167, v0
	v_cmp_gt_i32_e64 s[0:1], v167, v146
	s_and_b64 vcc, vcc, s[0:1]
	v_add_u32_e32 v167, 0x59, v166
	v_cndmask_b32_e32 v78, v209, v78, vcc
	v_cmp_le_i32_e32 vcc, v167, v0
	v_cmp_gt_i32_e64 s[0:1], v167, v146
	s_and_b64 vcc, vcc, s[0:1]
	v_add_u32_e32 v167, 0x5a, v166
	v_cndmask_b32_e32 v79, v209, v79, vcc
	v_cmp_le_i32_e32 vcc, v167, v0
	v_cmp_gt_i32_e64 s[0:1], v167, v146
	s_and_b64 vcc, vcc, s[0:1]
	v_add_u32_e32 v166, 0x5b, v166
	v_cndmask_b32_e32 v80, v209, v80, vcc
	v_cmp_le_i32_e32 vcc, v166, v0
	v_cmp_gt_i32_e64 s[0:1], v166, v146
	s_and_b64 vcc, vcc, s[0:1]
	v_cndmask_b32_e32 v81, v209, v81, vcc
